# prep_vt (V transpose) software-pipelined: both tile loads issued together, next iteration's loads issued after the first barrier
# speedup vs baseline: 1.0019x; 1.0019x over previous
.LBB0_326:
	s_or_b64 exec, exec, s[10:11]
	s_mov_b64 s[16:17], s[84:85]
	s_waitcnt lgkmcnt(0)
	v_mov_b32_e32 v0, v173
	s_barrier
	s_getreg_b32 s1, hwreg(HW_REG_HW_ID, 0, 7)
	s_and_b32 s1, s1, 63
	s_lshl_b32 s1, s1, 2
	v_mov_b32_e32 v1, s1
	ds_read_b32 v1, v1
	v_readlane_b32 s6, v254, 7
	v_readlane_b32 s7, v254, 8
	s_mov_b64 s[10:11], -1
	s_and_b64 vcc, exec, s[6:7]
	s_waitcnt lgkmcnt(0)
	v_readfirstlane_b32 s1, v1
	s_lshl_b32 s1, s1, 6
	s_and_b32 s1, s1, 0x3fc0
	v_add_u32_e32 v72, s1, v0
	s_cbranch_vccz .LBB0_335
	v_readlane_b32 s6, v254, 51
	v_readlane_b32 s7, v254, 52
	s_andn2_b64 vcc, exec, s[6:7]
	s_cbranch_vccnz .LBB0_334
	v_readfirstlane_b32 s42, v72
	s_cmpk_lt_u32 s42, 0x100
	s_cbranch_scc1 .Ls5_work
	s_cmpk_lt_u32 s42, 0x100
	s_cbranch_scc1 .LBB0_334
	s_load_dwordx2 s[42:43], s[16:17], 0xe0
	s_sub_u32 s48, s2, 32
	s_lshl_b32 s48, s48, 11
	v_and_b32_e32 v140, 0x7f, v72
	v_lshlrev_b32_e32 v140, 4, v140
	v_lshrrev_b32_e32 v141, 7, v72
	v_subrev_u32_e32 v141, 2, v141
	v_lshl_add_u32 v140, v141, 13, v140
	s_waitcnt lgkmcnt(0)
	s_add_u32 s42, s42, s48
	s_addc_u32 s43, s43, 0
	s_add_u32 s42, s42, 0xf100000
	s_addc_u32 s43, s43, 0
	s_movk_i32 s48, 128

.LBB0_342:
	s_mov_b64 s[12:13], s[84:85]
	v_mov_b32_e32 v0, v173
	s_getreg_b32 s1, hwreg(HW_REG_HW_ID, 0, 7)
	s_and_b32 s1, s1, 63
	s_lshl_b32 s1, s1, 2
	v_mov_b32_e32 v1, s1
	ds_read_b32 v1, v1
	s_and_b64 vcc, exec, s[10:11]
	s_waitcnt lgkmcnt(0)
	v_readfirstlane_b32 s7, v1
	s_cbranch_vccnz .LBB0_346
	v_readlane_b32 s8, v254, 53
	v_readlane_b32 s9, v254, 54
	s_andn2_b64 vcc, exec, s[8:9]
	s_cbranch_vccnz .LBB0_346
	s_load_dwordx2 s[8:9], s[12:13], 0xe0
	v_and_b32_e32 v1, 15, v0
	v_lshlrev_b32_e32 v6, 3, v0
	v_and_b32_e32 v14, 56, v6
	v_lshlrev_b32_e32 v12, 3, v1
	s_waitcnt lgkmcnt(0)
	s_add_u32 s10, s8, 0xc000000
	s_addc_u32 s11, s9, 0
	s_add_u32 s1, s8, 0x3000000
	s_addc_u32 s6, s9, 0
	s_lshl_b32 s7, s7, 6
	s_and_b32 s7, s7, 0x3fc0
	v_add_u32_e32 v4, s7, v0
	v_ashrrev_i32_e32 v2, 4, v4
	s_movk_i32 s7, 0x104
	v_mul_lo_u32 v3, v2, s7
	v_add_u32_e32 v9, 0x200, v4
	v_lshlrev_b32_e32 v0, 2, v0
	v_add_u32_e32 v11, 0x120, v3
	v_ashrrev_i32_e32 v3, 4, v9
	v_and_b32_e32 v0, 4, v0
	v_mul_lo_u32 v5, v3, s7
	v_and_or_b32 v6, v6, 48, v0
	v_or_b32_e32 v0, v0, v14
	v_lshlrev_b32_e32 v1, 4, v1
	v_add_u32_e32 v13, 0x120, v5
	v_ashrrev_i32_e32 v4, 3, v4
	v_or_b32_e32 v7, 8, v0
	v_or_b32_e32 v0, 10, v0
	v_ashrrev_i32_e32 v9, 3, v9
	v_lshl_add_u32 v5, v4, 1, v195
	v_mul_u32_u24_e32 v6, 0x104, v6
	v_mul_u32_u24_e32 v7, 0x104, v7
	v_mul_u32_u24_e32 v8, 0x104, v0
	v_lshl_add_u32 v10, v9, 1, v195
	v_lshlrev_b32_e32 v160, 1, v12
	v_add_u32_e32 v11, v11, v1
	v_add_u32_e32 v12, v13, v1
	v_lshlrev_b32_e32 v0, 1, v14
	v_readlane_b32 s7, v254, 47
	v_readlane_b32 s8, v254, 46
	v_mov_b32_e32 v13, v193
	s_and_b32 s16, s7, 0xffffffc0
	s_and_b32 s18, s8, 0x180
	s_lshl_b32 s18, s18, 1
	s_mov_b32 s19, 0
	v_mov_b64_e32 v[110:111], s[10:11]
	v_add_u32_e32 v112, s16, v2
	v_mad_i64_i32 v[108:109], s[14:15], v112, s78, v[110:111]
	v_lshl_add_u64 v[108:109], v[108:109], 0, s[18:19]
	v_lshl_add_u64 v[108:109], v[108:109], 0, v[160:161]
	global_load_dwordx4 v[100:103], v[108:109], off offset:2048
	v_add_u32_e32 v112, s16, v3
	v_mad_i64_i32 v[108:109], s[14:15], v112, s78, v[110:111]
	v_lshl_add_u64 v[108:109], v[108:109], 0, s[18:19]
	v_lshl_add_u64 v[108:109], v[108:109], 0, v[160:161]
	global_load_dwordx4 v[104:107], v[108:109], off offset:2048
	s_mov_b32 s17, 1
.LBB0_345:
	s_and_b32 s12, s7, 0xffffffc0
	s_and_b32 s9, s8, 0x180
	s_ashr_i32 s13, s12, 31
	s_lshl_b64 s[12:13], s[12:13], 1
	s_add_u32 s12, s1, s12
	s_addc_u32 s13, s6, s13
	v_add_u32_e32 v13, s79, v13
	v_cmp_gt_i32_e32 vcc, s90, v13
	s_add_i32 s8, s8, s95
	s_add_i32 s7, s7, s96
	s_and_b64 vcc, exec, vcc
	v_add_u32_e32 v1, v5, v6
	v_add_u32_e32 v18, s9, v4
	v_ashrrev_i32_e32 v19, 31, v18
	v_lshlrev_b64 v[18:19], 15, v[18:19]
	v_lshl_add_u64 v[18:19], s[12:13], 0, v[18:19]
	s_cmp_eq_u32 s17, 0
	s_mov_b32 s17, 0
	s_cbranch_scc1 .Lvt_w2
	s_waitcnt vmcnt(1)
	ds_write2_b32 v11, v100, v101 offset1:1
	ds_write2_b32 v11, v102, v103 offset0:2 offset1:3
	s_waitcnt vmcnt(0)
	s_branch .Lvt_w3
.Lvt_w2:
	s_waitcnt vmcnt(3)
	ds_write2_b32 v11, v100, v101 offset1:1
	ds_write2_b32 v11, v102, v103 offset0:2 offset1:3
	s_waitcnt vmcnt(2)
.Lvt_w3:
	ds_write2_b32 v12, v104, v105 offset1:1
	ds_write2_b32 v12, v106, v107 offset0:2 offset1:3
	s_waitcnt lgkmcnt(0)
	s_barrier
	s_cbranch_vccz .Lvt_nopf
	s_and_b32 s16, s7, 0xffffffc0
	s_and_b32 s18, s8, 0x180
	s_lshl_b32 s18, s18, 1
	s_mov_b32 s19, 0
	v_mov_b64_e32 v[110:111], s[10:11]
	v_add_u32_e32 v112, s16, v2
	v_mad_i64_i32 v[108:109], s[14:15], v112, s78, v[110:111]
	v_lshl_add_u64 v[108:109], v[108:109], 0, s[18:19]
	v_lshl_add_u64 v[108:109], v[108:109], 0, v[160:161]
	global_load_dwordx4 v[100:103], v[108:109], off offset:2048
	v_add_u32_e32 v112, s16, v3
	v_mad_i64_i32 v[108:109], s[14:15], v112, s78, v[110:111]
	v_lshl_add_u64 v[108:109], v[108:109], 0, s[18:19]
	v_lshl_add_u64 v[108:109], v[108:109], 0, v[160:161]
	global_load_dwordx4 v[104:107], v[108:109], off offset:2048
.Lvt_nopf:
	ds_read_u16 v14, v1
	ds_read_u16 v15, v1 offset:260
	s_waitcnt lgkmcnt(0)
	v_lshl_or_b32 v14, v15, 16, v14
	ds_read_u16 v15, v1 offset:520
	ds_read_u16 v1, v1 offset:780
	s_waitcnt lgkmcnt(0)
	v_lshl_or_b32 v15, v1, 16, v15
	v_add_u32_e32 v1, v5, v7
	ds_read_u16 v16, v1
	ds_read_u16 v1, v1 offset:260
	s_waitcnt lgkmcnt(0)
	v_lshl_or_b32 v16, v1, 16, v16
	v_add_u32_e32 v1, v5, v8
	ds_read_u16 v17, v1
	ds_read_u16 v1, v1 offset:260
	s_waitcnt lgkmcnt(0)
	v_lshl_or_b32 v17, v1, 16, v17
	v_mov_b32_e32 v1, v161
	v_lshl_add_u64 v[18:19], v[18:19], 0, v[0:1]
	global_store_dwordx4 v[18:19], v[14:17], off
	s_nop 1
	v_add_u32_e32 v15, v10, v6
	ds_read_u16 v14, v15
	ds_read_u16 v16, v15 offset:260
	s_waitcnt lgkmcnt(0)
	v_lshl_or_b32 v14, v16, 16, v14
	ds_read_u16 v16, v15 offset:520
	ds_read_u16 v15, v15 offset:780
	s_waitcnt lgkmcnt(0)
	v_lshl_or_b32 v15, v15, 16, v16
	v_add_u32_e32 v16, v10, v7
	ds_read_u16 v17, v16
	ds_read_u16 v16, v16 offset:260
	s_waitcnt lgkmcnt(0)
	v_lshl_or_b32 v16, v16, 16, v17
	v_add_u32_e32 v17, v10, v8
	ds_read_u16 v18, v17
	ds_read_u16 v17, v17 offset:260
	s_waitcnt lgkmcnt(0)
	v_lshl_or_b32 v17, v17, 16, v18
	v_add_u32_e32 v18, s9, v9
	v_ashrrev_i32_e32 v19, 31, v18
	v_lshlrev_b64 v[18:19], 15, v[18:19]
	v_lshl_add_u64 v[18:19], s[12:13], 0, v[18:19]
	v_lshl_add_u64 v[18:19], v[18:19], 0, v[0:1]
	global_store_dwordx4 v[18:19], v[14:17], off
	s_barrier
	s_cbranch_vccnz .LBB0_345
